# speedup vs baseline: 1.0099x; 1.0099x over previous
; template <int DUMMY>
; __device__ void ssd_item(const Params& p, int item) {
;     ...
;   auto load_raw = [&](int c) {
; #pragma unroll
;     for (int i = 0; i < 2; ++i) {
;       int idx = tid + i * NT;
;       const u16* rp = bc + (tb + c * 64 + (idx >> 4)) * 2048 + grp * 128 + (idx & 15) * 8;
;       rBs[i] = *(const i32x4*)rp;
;       rCs[i] = *(const i32x4*)(rp + 1024);
;       rBT[i] = *(const i32x4*)(bc + (tb + c * 64 + (idx & 63)) * 2048 + grp * 128 + (idx >> 6) * 8);
;     }
; #pragma unroll
;     for (int i = 0; i < 7; ++i) {
;       int row = c * 64 + l0 - 3 + i;
;       rX[i] = row >= 0 ? xbc[(tb + row) * 6144 + colX + chg] : (u16)0;
;     }
;   };
.LBB0_934:
	s_or_b64 exec, exec, s[4:5]
	s_ashr_i32 s30, s7, 3
	s_ashr_i32 s31, s30, 31
	v_ashrrev_i32_e32 v78, 4, v40
	v_add_u32_e32 v22, 0x200, v40
	v_and_b32_e32 v98, 63, v40
	s_lshl_b64 s[64:65], s[30:31], 13
	v_ashrrev_i32_e32 v79, 31, v78
	v_ashrrev_i32_e32 v80, 4, v22
	v_lshl_add_u64 v[0:1], s[64:65], 0, v[78:79]
	s_lshl_b32 s0, s68, 4
	v_or_b32_e32 v46, s64, v98
	v_mov_b32_e32 v47, s65
	v_ashrrev_i32_e32 v81, 31, v80
	v_ashrrev_i32_e32 v44, 3, v40
	v_lshlrev_b64 v[24:25], 12, v[0:1]
	s_and_b32 s0, s0, 0x380
	v_lshlrev_b32_e32 v2, 3, v40
	v_lshlrev_b64 v[28:29], 12, v[46:47]
	v_lshl_add_u64 v[12:13], s[64:65], 0, v[80:81]
	v_lshl_add_u64 v[0:1], s[40:41], 0, v[24:25]
	s_lshl_b32 s58, s0, 1
	v_and_b32_e32 v59, 0x78, v2
	v_lshl_add_u64 v[8:9], s[40:41], 0, v[28:29]
	v_and_b32_e32 v62, -8, v44
	v_lshlrev_b64 v[30:31], 12, v[12:13]
	v_lshl_add_u64 v[0:1], v[0:1], 0, s[58:59]
	v_lshlrev_b32_e32 v54, 1, v59
	v_mov_b32_e32 v55, v41
	v_lshl_add_u64 v[8:9], v[8:9], 0, s[58:59]
	v_ashrrev_i32_e32 v63, 31, v62
	v_lshl_add_u64 v[12:13], s[40:41], 0, v[30:31]
	v_lshl_add_u64 v[4:5], v[0:1], 0, v[54:55]
	v_lshl_add_u64 v[10:11], v[62:63], 1, v[8:9]
	v_lshl_add_u64 v[12:13], v[12:13], 0, s[58:59]
	global_load_dwordx4 v[0:3], v[4:5], off
	s_nop 0
	global_load_dwordx4 v[4:7], v[4:5], off offset:2048
	v_lshl_add_u64 v[20:21], v[12:13], 0, v[54:55]
	global_load_dwordx4 v[16:19], v[10:11], off
	global_load_dwordx4 v[12:15], v[20:21], off
	v_ashrrev_i32_e32 v10, 3, v22
	v_and_b32_e32 v64, -8, v10
	v_ashrrev_i32_e32 v65, 31, v64
	v_lshl_add_u64 v[8:9], v[64:65], 1, v[8:9]
	global_load_dwordx4 v[20:23], v[20:21], off offset:2048
	s_nop 0
	global_load_dwordx4 v[8:11], v[8:9], off
	v_and_b32_e32 v50, -4, v44
	v_cmp_lt_i32_e32 vcc, 3, v44
	v_mov_b32_e32 v33, 0
	v_mov_b32_e32 v32, 0
	v_mov_b32_e32 v216, 0
	v_mov_b32_e32 v217, 0
	v_mov_b32_e32 v218, 0
	v_mov_b32_e32 v219, 0
	v_mov_b32_e32 v220, 0
	v_mov_b32_e32 v221, 0
	v_mov_b32_e32 v222, 0
	s_and_saveexec_b64 s[0:1], vcc
	s_cbranch_execz .LBB0_936
	v_add_u32_e32 v36, -3, v50
	v_mov_b32_e32 v37, v41
	v_lshl_add_u64 v[36:37], s[64:65], 0, v[36:37]
	v_mov_b64_e32 v[38:39], s[46:47]
	v_mad_u64_u32 v[38:39], s[4:5], v36, s86, v[38:39]
	v_mad_i32_i24 v39, v37, s86, v39
	s_lshl_b32 s4, s3, 1
	s_mov_b32 s5, s59
	v_mov_b32_e32 v27, v41
	v_lshl_add_u64 v[36:37], v[38:39], 0, s[4:5]
	v_lshl_add_u64 v[36:37], v[26:27], 1, v[36:37]
	global_load_ushort v216, v[36:37], off
.LBB0_936:
	s_or_b64 exec, exec, s[0:1]
	s_and_saveexec_b64 s[0:1], vcc
	s_cbranch_execz .LBB0_938
	v_add_u32_e32 v36, -2, v50
	v_mov_b32_e32 v37, v41
	v_lshl_add_u64 v[36:37], s[64:65], 0, v[36:37]
	v_mov_b64_e32 v[38:39], s[46:47]
	v_mad_u64_u32 v[38:39], s[4:5], v36, s86, v[38:39]
	v_mad_i32_i24 v39, v37, s86, v39
	s_lshl_b32 s4, s3, 1
	s_mov_b32 s5, s59
	v_mov_b32_e32 v27, v41
	v_lshl_add_u64 v[36:37], v[38:39], 0, s[4:5]
	v_lshl_add_u64 v[36:37], v[26:27], 1, v[36:37]
	global_load_ushort v217, v[36:37], off
.LBB0_938:
	s_or_b64 exec, exec, s[0:1]
	v_mov_b32_e32 v35, 0
	v_mov_b32_e32 v37, 0
	s_and_saveexec_b64 s[0:1], vcc
	s_cbranch_execz .LBB0_940
	v_add_u32_e32 v36, -1, v50
	v_mov_b32_e32 v37, v41
	v_lshl_add_u64 v[36:37], s[64:65], 0, v[36:37]
	v_mov_b64_e32 v[38:39], s[46:47]
	v_mad_u64_u32 v[38:39], s[4:5], v36, s86, v[38:39]
	v_mad_i32_i24 v39, v37, s86, v39
	s_lshl_b32 s4, s3, 1
	s_mov_b32 s5, s59
	v_mov_b32_e32 v27, v41
	v_lshl_add_u64 v[36:37], v[38:39], 0, s[4:5]
	v_lshl_add_u64 v[36:37], v[26:27], 1, v[36:37]
	global_load_ushort v218, v[36:37], off
.LBB0_940:
	s_or_b64 exec, exec, s[0:1]
	v_cmp_lt_i32_e32 vcc, -1, v44
	s_and_saveexec_b64 s[0:1], vcc
	s_cbranch_execz .LBB0_942
	v_mov_b32_e32 v51, v41
	v_lshl_add_u64 v[38:39], s[64:65], 0, v[50:51]
	v_mov_b64_e32 v[48:49], s[46:47]
	v_mad_u64_u32 v[48:49], s[4:5], v38, s86, v[48:49]
	v_mad_i32_i24 v49, v39, s86, v49
	s_lshl_b32 s4, s3, 1
	s_mov_b32 s5, s59
	v_mov_b32_e32 v27, v41
	v_lshl_add_u64 v[38:39], v[48:49], 0, s[4:5]
	v_lshl_add_u64 v[38:39], v[26:27], 1, v[38:39]
	global_load_ushort v219, v[38:39], off
.LBB0_942:
	s_or_b64 exec, exec, s[0:1]
	v_mov_b32_e32 v39, 0
	v_mov_b32_e32 v83, 0
	s_and_saveexec_b64 s[0:1], vcc
	s_cbranch_execz .LBB0_944
	v_or_b32_e32 v48, 1, v50
	v_mov_b32_e32 v49, v41
	v_lshl_add_u64 v[48:49], s[64:65], 0, v[48:49]
	v_mov_b64_e32 v[52:53], s[46:47]
	v_mad_u64_u32 v[52:53], s[4:5], v48, s86, v[52:53]
	v_mad_i32_i24 v53, v49, s86, v53
	s_lshl_b32 s4, s3, 1
	s_mov_b32 s5, s59
	v_mov_b32_e32 v27, v41
	v_lshl_add_u64 v[48:49], v[52:53], 0, s[4:5]
	v_lshl_add_u64 v[48:49], v[26:27], 1, v[48:49]
	global_load_ushort v220, v[48:49], off
.LBB0_944:
	s_or_b64 exec, exec, s[0:1]
	s_and_saveexec_b64 s[0:1], vcc
	s_cbranch_execz .LBB0_946
	v_or_b32_e32 v38, 2, v50
	v_mov_b32_e32 v39, v41
	v_lshl_add_u64 v[38:39], s[64:65], 0, v[38:39]
	v_mov_b64_e32 v[48:49], s[46:47]
	v_mad_u64_u32 v[48:49], s[4:5], v38, s86, v[48:49]
	v_mad_i32_i24 v49, v39, s86, v49
	s_lshl_b32 s4, s3, 1
	s_mov_b32 s5, s59
	v_mov_b32_e32 v27, v41
	v_lshl_add_u64 v[38:39], v[48:49], 0, s[4:5]
	v_lshl_add_u64 v[38:39], v[26:27], 1, v[38:39]
	global_load_ushort v221, v[38:39], off
.LBB0_946:
	s_or_b64 exec, exec, s[0:1]
	v_mov_b32_e32 v118, 0
	v_mov_b32_e32 v85, 0
	s_and_saveexec_b64 s[0:1], vcc
	s_cbranch_execz .LBB0_948
	v_or_b32_e32 v48, 3, v44
	v_mov_b32_e32 v49, v41
	v_lshl_add_u64 v[48:49], s[64:65], 0, v[48:49]
	v_mov_b64_e32 v[52:53], s[46:47]
	v_mad_u64_u32 v[52:53], s[4:5], v48, s86, v[52:53]
	v_mad_i32_i24 v53, v49, s86, v53
	s_lshl_b32 s4, s3, 1
	s_mov_b32 s5, s59
	v_mov_b32_e32 v27, v41
	v_lshl_add_u64 v[48:49], v[52:53], 0, s[4:5]
	v_lshl_add_u64 v[48:49], v[26:27], 1, v[48:49]
	global_load_ushort v222, v[48:49], off
; __device__ __forceinline__ float bf2f(u16 h) { return __uint_as_float(((unsigned)h) << 16); }
; template <int DUMMY>
; __device__ void ssd_item(const Params& p, int item) {
;     ...
;   load_raw(0);
;   float dt_n = 0.f;
;   if (wid == 0) {
;     float dt0 = dtb[(tb + lane) * 64 + h];
;     dt_n = dtb[(tb + 64 + lane) * 64 + h];
;     write_cs(dt0, 0);
;   }
;   f32x4 accS[2];
;   accS[0] = f32x4{0.f, 0.f, 0.f, 0.f};
;   accS[1] = f32x4{0.f, 0.f, 0.f, 0.f};
;   const int lf = wid >> 1, pf = wid & 1;
;   const int nf0 = (wid >> 1) * 2;
;   u16 znext[4], zcur[4];
;   i32x2 ypend = {0, 0};
;   size_t zbase = (tb + lf * 16 + g4 * 4) * 4096 + h * 64 + ph * 32 + pf * 16 + fr;
; #pragma unroll
;   for (int r = 0; r < 4; ++r) { znext[r] = zy[zbase + (size_t)r * 4096]; zcur[r] = 0; }
;   __syncthreads();
;   int cur3 = 0;
;   for (int c = 0; c < 128; ++c) {
;     const int par = c & 1;
;     const int nxt3 = cur3 == 2 ? 0 : cur3 + 1;
;     u16* const Cs = par ? Cs1 : Cs0;
;     u16* const xdT = par ? xdT1 : xdT0;
;     u16* const xT = par ? xT1 : xT0;
;     u16* const Sb = par ? Sb1 : Sb0;
;     const float* cs = csb + cur3 * 64;
;     const float* dv = dtv + cur3 * 64;
;     {
; #pragma unroll
;       for (int i = 0; i < 2; ++i) {
;         int idx = tid + i * NT;
;         *(i32x4*)(Bs + (idx >> 4) * 136 + (idx & 15) * 8) = rBs[i];
;         *(i32x4*)(Cs + (idx >> 4) * 136 + (idx & 15) * 8) = rCs[i];
;         int c8 = idx >> 6, ll = idx & 63;
; #pragma unroll
;         for (int e = 0; e < 4; ++e) {
;           unsigned u = (unsigned)rBT[i][e];
;           BTs[(c8 * 8 + 2 * e) * 72 + ll] = (u16)(u & 0xffffu);
;           BTs[(c8 * 8 + 2 * e + 1) * 72 + ll] = (u16)(u >> 16);
;         }
;       }
;       {
;         float w0 = cwX[0 * 32 + chg], w1 = cwX[1 * 32 + chg], w2 = cwX[2 * 32 + chg], w3 = cwX[3 * 32 + chg], bx = cwX[4 * 32 + chg];
;         float raw[7];
; #pragma unroll
;         for (int i = 0; i < 7; ++i) raw[i] = bf2f(rX[i]);
;         const float cs63 = cs[63];
;         float4 dt4 = *(const float4*)(dv + l0), cs4 = *(const float4*)(cs + l0);
;         float dts[4] = {dt4.x, dt4.y, dt4.z, dt4.w}, css[4] = {cs4.x, cs4.y, cs4.z, cs4.w};
.LBB0_948:
	s_or_b64 exec, exec, s[0:1]
	s_waitcnt vmcnt(0)
	v_lshlrev_b32_e32 v32, 16, v216
	v_lshlrev_b32_e32 v33, 16, v217
	v_lshlrev_b32_e32 v37, 16, v218
	v_lshlrev_b32_e32 v35, 16, v219
	v_lshlrev_b32_e32 v83, 16, v220
	v_lshlrev_b32_e32 v39, 16, v221
	v_lshlrev_b32_e32 v85, 16, v222
	s_waitcnt vmcnt(7)
	v_mul_f32_e32 v27, 0x3fb8aa3b, v34
	v_exp_f32_e32 v120, v27
	v_cmp_gt_u32_e64 s[4:5], 64, v40
	s_and_saveexec_b64 s[0:1], s[4:5]
	s_cbranch_execz .LBB0_950
	v_lshlrev_b64 v[46:47], 8, v[46:47]
	v_lshl_add_u64 v[46:47], s[54:55], 0, v[46:47]
	s_mov_b32 s7, s59
	v_lshl_add_u64 v[46:47], v[46:47], 0, s[6:7]
	global_load_dword v27, v[46:47], off
	v_add_co_u32_e32 v46, vcc, 0x4000, v46
	v_lshlrev_b32_e32 v34, 2, v98
	s_nop 0
	v_addc_co_u32_e32 v47, vcc, 0, v47, vcc
	global_load_dword v118, v[46:47], off
	v_cmp_lt_u32_e32 vcc, 15, v40
	v_or_b32_e32 v36, 0x1e200, v34
	v_or_b32_e32 v34, 0x1e500, v34
	s_waitcnt vmcnt(1)
	v_mul_f32_e64 v38, v27, -v120
	s_nop 1
	v_mov_b32_dpp v38, v38 row_shr:1 row_mask:0xf bank_mask:0xf bound_ctrl:1
	v_fma_f32 v38, v27, -v120, v38
	s_nop 1
	v_add_f32_dpp v38, v38, v38 row_shr:2 row_mask:0xf bank_mask:0xf bound_ctrl:1
	s_nop 1
	v_add_f32_dpp v38, v38, v38 row_shr:4 row_mask:0xf bank_mask:0xf bound_ctrl:1
	s_nop 1
	v_add_f32_dpp v38, v38, v38 row_shr:8 row_mask:0xf bank_mask:0xf bound_ctrl:1
	s_nop 0
	v_readlane_b32 s7, v38, 15
	v_readlane_b32 s8, v38, 31
	v_readlane_b32 s9, v38, 47
	v_mov_b32_e32 v42, s7
	v_mov_b32_e32 v45, s8
	v_cndmask_b32_e32 v42, 0, v42, vcc
	v_cmp_lt_u32_e32 vcc, 31, v40
	v_mov_b32_e32 v46, s9
	s_nop 0
	v_cndmask_b32_e32 v45, 0, v45, vcc
	v_cmp_lt_u32_e32 vcc, 47, v40
	v_add_f32_e32 v42, v42, v45
	s_nop 0
	v_cndmask_b32_e32 v46, 0, v46, vcc
	v_add_f32_e32 v42, v46, v42
	v_add_f32_e32 v38, v38, v42
	ds_write_b32 v36, v38
	ds_write_b32 v34, v27
.LBB0_950:
	s_or_b64 exec, exec, s[0:1]
	v_ashrrev_i32_e32 v96, 7, v40
	v_lshlrev_b32_e32 v46, 4, v96
	v_lshrrev_b32_e32 v58, 4, v98
	v_ashrrev_i32_e32 v47, 31, v46
	v_lshl_add_u64 v[76:77], s[64:65], 0, v[46:47]
	v_lshlrev_b32_e32 v48, 2, v58
	v_bfe_u32 v45, v40, 6, 1
	v_or_b32_e32 v76, v76, v48
	v_lshlrev_b64 v[52:53], 12, v[76:77]
	v_lshlrev_b32_e32 v60, 4, v45
	v_and_b32_e32 v56, 15, v40
	v_or_b32_e32 v27, v52, v60
	v_or3_b32 v27, v27, v56, s75
	v_or_b32_e32 v52, s74, v27
	v_lshl_add_u64 v[74:75], v[52:53], 1, s[48:49]
	s_movk_i32 s0, 0x2000
	v_add_co_u32_e32 v52, vcc, s0, v74
	s_movk_i32 s0, 0x4000
	s_nop 0
	v_addc_co_u32_e32 v53, vcc, 0, v75, vcc
	v_add_co_u32_e32 v66, vcc, s0, v74
	s_add_u32 s0, s40, s58
	s_nop 0
	v_addc_co_u32_e32 v67, vcc, 0, v75, vcc
	s_addc_u32 s1, s41, 0
	s_lshl_b32 s3, s3, 1
	v_add_co_u32_e32 v68, vcc, s85, v74
	v_mov_b32_e32 v55, v41
	s_add_u32 s8, s46, s3
	v_addc_co_u32_e32 v69, vcc, 0, v75, vcc
	v_lshlrev_b32_e32 v34, 1, v98
	v_mov_b32_e32 v27, v41
	v_lshl_add_u64 v[70:71], s[0:1], 0, v[54:55]
	s_addc_u32 s9, s47, 0
	v_mul_lo_u32 v146, v78, s88
	v_mul_lo_u32 v147, v80, s88
	global_load_ushort v94, v[74:75], off
	global_load_ushort v42, v[52:53], off
	global_load_ushort v90, v[66:67], off
	global_load_ushort v88, v[68:69], off
	v_lshl_add_u64 v[66:67], v[26:27], 1, s[8:9]
	v_lshl_add_u32 v116, v146, 1, v54
	v_mad_u64_u32 v[52:53], s[8:9], v62, s89, v[34:35]
	v_lshl_add_u32 v117, v147, 1, v54
	v_mad_u64_u32 v[54:55], s[8:9], v64, s89, v[34:35]
	v_lshl_add_u64 v[68:69], v[70:71], 0, v[24:25]
	s_mov_b32 s3, 0x40000
	s_waitcnt lgkmcnt(0)
	s_barrier
	s_waitcnt vmcnt(9)
	ds_write_b128 v116, v[0:3] offset:17408
	s_waitcnt vmcnt(8)
	ds_write_b128 v116, v[4:7]
	s_waitcnt vmcnt(7)
	ds_write_b16 v52, v16 offset:34816
	ds_write_b16_d16_hi v52, v16 offset:34960
	ds_write_b16 v52, v17 offset:35104
	ds_write_b16_d16_hi v52, v17 offset:35248
	ds_write_b16 v52, v18 offset:35392
	ds_write_b16_d16_hi v52, v18 offset:35536
	ds_write_b16 v52, v19 offset:35680
	ds_write_b16_d16_hi v52, v19 offset:35824
	s_waitcnt vmcnt(6)
	ds_write_b128 v117, v[12:15] offset:17408
	s_waitcnt vmcnt(5)
	ds_write_b128 v117, v[20:23]
	s_waitcnt vmcnt(4)
	ds_write_b16 v54, v8 offset:34816
	ds_write_b16_d16_hi v54, v8 offset:34960
	ds_write_b16 v54, v9 offset:35104
	ds_write_b16_d16_hi v54, v9 offset:35248
	ds_write_b16 v54, v10 offset:35392
	ds_write_b16_d16_hi v54, v10 offset:35536
	ds_write_b16 v54, v11 offset:35680
	ds_write_b16_d16_hi v54, v11 offset:35824
	v_add_co_u32_e32 v8, vcc, s3, v68
	v_lshl_add_u64 v[72:73], s[0:1], 0, v[28:29]
	s_nop 0
	v_addc_co_u32_e32 v9, vcc, 0, v69, vcc
	s_mov_b64 s[0:1], 0x40000
	v_lshl_add_u64 v[70:71], v[70:71], 0, v[30:31]
	v_lshl_add_u64 v[16:17], v[72:73], 0, s[0:1]
	v_add_co_u32_e32 v28, vcc, 0x40000, v70
	v_lshl_add_u32 v115, v26, 2, v102
	v_lshlrev_b32_e32 v36, 2, v50
	v_lshl_add_u64 v[18:19], v[62:63], 1, v[16:17]
	v_addc_co_u32_e32 v29, vcc, 0, v71, vcc
	v_lshl_add_u64 v[16:17], v[64:65], 1, v[16:17]
	v_add_u32_e32 v114, 0x1e500, v36
	v_mul_u32_u24_e32 v143, 0x48, v26
	ds_read2_b32 v[4:5], v115 offset1:32
	ds_read2_b32 v[6:7], v115 offset0:64 offset1:96
	ds_read_b32 v38, v115 offset:512
	ds_read_b32 v51, v103
	ds_read_b128 v[0:3], v114
	global_load_dwordx4 v[12:15], v[8:9], off
	s_nop 0
	global_load_dwordx4 v[8:11], v[8:9], off offset:2048
	s_nop 0
	global_load_dwordx4 v[20:23], v[18:19], off
	global_load_dwordx4 v[24:27], v[28:29], off
	s_nop 0
	global_load_dwordx4 v[28:31], v[28:29], off offset:2048
	s_nop 0
	global_load_dwordx4 v[16:19], v[16:17], off
	v_add_u32_e32 v49, 0x1e200, v36
	s_waitcnt lgkmcnt(2)
; __device__ __forceinline__ float bf2f(u16 h) { return __uint_as_float(((unsigned)h) << 16); }
; __device__ __forceinline__ float siluf_(float v) { return v * __builtin_amdgcn_rcpf(1.f + __expf(-v)); }
; template <int DUMMY>
; __device__ void ssd_item(const Params& p, int item) {
;     ...
; #pragma unroll
;     for (int i = 0; i < 7; ++i) {
;       int row = c * 64 + l0 - 3 + i;
;       rX[i] = row >= 0 ? xbc[(tb + row) * 6144 + colX + chg] : (u16)0;
;     }
;     ...
;         float w0 = cwX[0 * 32 + chg], w1 = cwX[1 * 32 + chg], w2 = cwX[2 * 32 + chg], w3 = cwX[3 * 32 + chg], bx = cwX[4 * 32 + chg];
;         float raw[7];
; #pragma unroll
;         for (int i = 0; i < 7; ++i) raw[i] = bf2f(rX[i]);
;         const float cs63 = cs[63];
;         float4 dt4 = *(const float4*)(dv + l0), cs4 = *(const float4*)(cs + l0);
;         float dts[4] = {dt4.x, dt4.y, dt4.z, dt4.w}, css[4] = {cs4.x, cs4.y, cs4.z, cs4.w};
;         float vx[4], vd[4], vw[4];
; #pragma unroll
;         for (int j = 0; j < 4; ++j) {
;           float s = bx + w0 * raw[j] + w1 * raw[j + 1] + w2 * raw[j + 2] + w3 * raw[j + 3];
;           vx[j] = siluf_(s);
;           vd[j] = vx[j] * dts[j];
;           vw[j] = vd[j] * __expf(cs63 - css[j]);
;         }
;         *(i32x2*)(xT + chg * 72 + l0) = i32x2{(int)pack2(vx[0], vx[1]), (int)pack2(vx[2], vx[3])};
;         *(i32x2*)(xdT + chg * 72 + l0) = i32x2{(int)pack2(vd[0], vd[1]), (int)pack2(vd[2], vd[3])};
;         *(i32x2*)(xwT + chg * 72 + l0) = i32x2{(int)pack2(vw[0], vw[1]), (int)pack2(vw[2], vw[3])};
;       }
;     }
; #pragma unroll
;     for (int j = 0; j < 2; ++j)
; #pragma unroll
;       for (int r = 0; r < 4; ++r) Sb[(pf * 16 + g4 * 4 + r) * 136 + (nf0 + j) * 16 + fr] = f2bf(accS[j][r]);
	v_pk_fma_f32 v[92:93], v[32:33], v[4:5], v[38:39] op_sel_hi:[1,0,0]
	v_mov_b32_e32 v36, v33
	v_mov_b32_e32 v32, v5
	v_pk_fma_f32 v[92:93], v[36:37], v[32:33], v[92:93] op_sel_hi:[1,0,1]
	v_mov_b32_e32 v34, v37
	v_pk_fma_f32 v[36:37], v[34:35], v[6:7], v[92:93] op_sel_hi:[1,0,1]
	v_mov_b32_e32 v82, v35
	v_mov_b32_e32 v92, v7
	v_pk_fma_f32 v[36:37], v[82:83], v[92:93], v[36:37] op_sel_hi:[1,0,1]
	ds_read_b128 v[122:125], v49
	v_mul_f32_e32 v5, 0xbfb8aa3b, v36
	v_exp_f32_e32 v5, v5
	v_mul_f32_e32 v7, 0xbfb8aa3b, v37
	v_exp_f32_e32 v7, v7
	v_mov_b32_e32 v84, v39
	v_add_f32_e32 v5, 1.0, v5
	v_rcp_f32_e32 v100, v5
	v_add_f32_e32 v5, 1.0, v7
	v_rcp_f32_e32 v101, v5
	s_waitcnt lgkmcnt(0)
	v_sub_f32_e32 v5, v51, v122
	v_mul_f32_e32 v5, 0x3fb8aa3b, v5
	v_exp_f32_e32 v122, v5
	v_sub_f32_e32 v5, v51, v123
	v_mul_f32_e32 v5, 0x3fb8aa3b, v5
	v_exp_f32_e32 v123, v5
	v_sub_f32_e32 v5, v51, v124
	v_mul_f32_e32 v7, 0x3fb8aa3b, v5
	v_pk_fma_f32 v[4:5], v[34:35], v[4:5], v[38:39] op_sel_hi:[1,0,0]
	v_mov_b32_e32 v38, v83
	v_pk_fma_f32 v[4:5], v[82:83], v[32:33], v[4:5] op_sel_hi:[1,0,1]
	v_pk_mul_f32 v[36:37], v[36:37], v[100:101]
	v_pk_fma_f32 v[4:5], v[38:39], v[6:7], v[4:5] op_sel_hi:[1,0,1]
	v_lshlrev_b32_e32 v144, 1, v50
	v_pk_fma_f32 v[4:5], v[84:85], v[92:93], v[4:5] op_sel_hi:[1,0,1]
	v_pk_mul_f32 v[0:1], v[0:1], v[36:37]
	v_mul_f32_e32 v6, 0xbfb8aa3b, v4
	v_exp_f32_e32 v32, v6
	v_mul_f32_e32 v6, 0xbfb8aa3b, v5
	v_exp_f32_e32 v33, v6
	v_exp_f32_e32 v6, v7
	v_add_f32_e32 v7, 1.0, v32
	v_rcp_f32_e32 v32, v7
	v_add_f32_e32 v7, 1.0, v33
	v_rcp_f32_e32 v33, v7
	v_sub_f32_e32 v7, v51, v125
	v_mul_f32_e32 v7, 0x3fb8aa3b, v7
	v_exp_f32_e32 v7, v7
	v_pk_mul_f32 v[4:5], v[4:5], v[32:33]
	v_lshl_add_u32 v113, v143, 1, v144
	v_pk_mul_f32 v[2:3], v[2:3], v[4:5]
	v_pk_mul_f32 v[34:35], v[122:123], v[0:1]
	v_pk_mul_f32 v[6:7], v[2:3], v[6:7]
	v_cvt_pk_bf16_f32 v32, v36, v37
	v_cvt_pk_bf16_f32 v33, v4, v5
	ds_write_b64 v113, v[32:33] offset:62464
	v_cvt_pk_bf16_f32 v0, v0, v1
	v_cvt_pk_bf16_f32 v1, v2, v3
	v_cvt_pk_bf16_f32 v2, v34, v35
	v_cvt_pk_bf16_f32 v3, v6, v7
	v_lshl_or_b32 v32, v96, 1, 1
	ds_write2st64_b64 v113, v[0:1], v[2:3] offset0:104 offset1:113
	v_lshl_or_b32 v0, v56, 1, v104
	v_lshlrev_b32_e32 v55, 6, v96
	v_lshlrev_b32_e32 v153, 5, v32
	v_or_b32_e32 v86, v60, v48
	v_add_u32_e32 v53, v0, v55
	v_add_u32_e32 v51, v0, v153
	v_mad_u32_u24 v1, v86, s90, v53
	v_mad_u32_u24 v0, v86, s90, v51
	s_movk_i32 s0, 0xffc2
	ds_write_b16 v1, v41
	ds_write_b16 v1, v41 offset:272
	ds_write_b16 v1, v41 offset:544
	ds_write_b16 v1, v41 offset:816
	ds_write_b16 v0, v41
	ds_write_b16 v0, v41 offset:272
	ds_write_b16 v0, v41 offset:544
	ds_write_b16 v0, v41 offset:816
	v_add_u32_e32 v0, 61, v50
	v_cmp_lt_i32_e32 vcc, s0, v50
	v_mov_b32_e32 v93, 0
	v_mov_b32_e32 v92, 0
	v_mov_b32_e32 v216, 0
	v_mov_b32_e32 v217, 0
	v_mov_b32_e32 v218, 0
	v_mov_b32_e32 v219, 0
	v_mov_b32_e32 v220, 0
	v_mov_b32_e32 v221, 0
	v_mov_b32_e32 v222, 0
	s_and_saveexec_b64 s[0:1], vcc
	s_cbranch_execz .LBB0_952
	v_mov_b32_e32 v1, v41
	v_lshl_add_u64 v[2:3], s[64:65], 0, v[0:1]
	v_mad_u64_u32 v[4:5], s[8:9], v2, s86, v[66:67]
	v_mad_i32_i24 v5, v3, s86, v5
	global_load_ushort v216, v[4:5], off
.LBB0_952:
	s_or_b64 exec, exec, s[0:1]
	s_movk_i32 s0, 0xffc1
	v_cmp_lt_i32_e64 s[0:1], s0, v50
	s_and_saveexec_b64 s[8:9], s[0:1]
	s_cbranch_execz .LBB0_954
	v_add_u32_e32 v2, 62, v50
	v_mov_b32_e32 v3, v41
	v_lshl_add_u64 v[2:3], s[64:65], 0, v[2:3]
	v_mad_u64_u32 v[4:5], s[0:1], v2, s86, v[66:67]
	v_mad_i32_i24 v5, v3, s86, v5
	global_load_ushort v217, v[4:5], off
.LBB0_954:
	s_or_b64 exec, exec, s[8:9]
	v_mov_b32_e32 v85, 0
	v_mov_b32_e32 v95, 0
	s_and_saveexec_b64 s[0:1], vcc
	s_cbranch_execz .LBB0_956
	v_or_b32_e32 v0, 2, v0
	v_mov_b32_e32 v1, v41
	v_lshl_add_u64 v[0:1], s[64:65], 0, v[0:1]
	v_mad_u64_u32 v[2:3], s[8:9], v0, s86, v[66:67]
	v_mad_i32_i24 v3, v1, s86, v3
	global_load_ushort v218, v[2:3], off
; template <int DUMMY>
; __device__ void ssd_item(const Params& p, int item) {
;     ...
; #pragma unroll
;     for (int i = 0; i < 7; ++i) {
;       int row = c * 64 + l0 - 3 + i;
;       rX[i] = row >= 0 ? xbc[(tb + row) * 6144 + colX + chg] : (u16)0;
;     }
;     ...
;     if (c + 1 < 128) {
;       load_raw(c + 1);
;       const size_t zn = zbase + (size_t)64 * 4096;
; #pragma unroll
;       for (int r = 0; r < 4; ++r) znext[r] = zy[zn + (size_t)r * 4096];
;       if (wid == 0) {
;         float dt_use = dt_n;
;         if (c + 2 < 128) dt_n = dtb[(tb + (c + 2) * 64 + lane) * 64 + h];
;         write_cs(dt_use, nxt3);
;       }
.LBB0_956:
	s_or_b64 exec, exec, s[0:1]
	s_movk_i32 s0, 0xffbf
	v_cmp_lt_i32_e32 vcc, s0, v50
	s_and_saveexec_b64 s[0:1], vcc
	s_cbranch_execz .LBB0_958
	v_add_u32_e32 v0, 64, v50
	v_mov_b32_e32 v1, v41
	v_lshl_add_u64 v[0:1], s[64:65], 0, v[0:1]
	v_mad_u64_u32 v[2:3], s[8:9], v0, s86, v[66:67]
	v_mad_i32_i24 v3, v1, s86, v3
	global_load_ushort v219, v[2:3], off
.LBB0_958:
	s_or_b64 exec, exec, s[0:1]
	s_movk_i32 s0, 0xffbe
	v_cmp_lt_i32_e32 vcc, s0, v50
	v_mov_b32_e32 v87, 0
	v_mov_b32_e32 v89, 0
	s_and_saveexec_b64 s[0:1], vcc
	s_cbranch_execz .LBB0_960
	v_add_u32_e32 v0, 0x41, v50
	v_mov_b32_e32 v1, v41
	v_lshl_add_u64 v[0:1], s[64:65], 0, v[0:1]
	v_mad_u64_u32 v[2:3], s[8:9], v0, s86, v[66:67]
	v_mad_i32_i24 v3, v1, s86, v3
	global_load_ushort v220, v[2:3], off
.LBB0_960:
	s_or_b64 exec, exec, s[0:1]
	s_movk_i32 s0, 0xffbd
	v_cmp_lt_i32_e32 vcc, s0, v50
	s_and_saveexec_b64 s[0:1], vcc
	s_cbranch_execz .LBB0_962
	v_add_u32_e32 v0, 0x42, v50
	v_mov_b32_e32 v1, v41
	v_lshl_add_u64 v[0:1], s[64:65], 0, v[0:1]
	v_mad_u64_u32 v[2:3], s[8:9], v0, s86, v[66:67]
	v_mad_i32_i24 v3, v1, s86, v3
	global_load_ushort v221, v[2:3], off
.LBB0_962:
	s_or_b64 exec, exec, s[0:1]
	s_movk_i32 s0, 0xffbc
	v_cmp_lt_i32_e32 vcc, s0, v50
	v_mov_b32_e32 v91, 0
	s_and_saveexec_b64 s[0:1], vcc
	s_cbranch_execz .LBB0_964
	v_add_u32_e32 v0, 0x43, v50
	v_mov_b32_e32 v1, v41
	v_lshl_add_u64 v[0:1], s[64:65], 0, v[0:1]
	v_mad_u64_u32 v[2:3], s[8:9], v0, s86, v[66:67]
	v_mad_i32_i24 v3, v1, s86, v3
	global_load_ushort v222, v[2:3], off
.LBB0_964:
	s_or_b64 exec, exec, s[0:1]
	s_waitcnt vmcnt(0)
	v_lshlrev_b32_e32 v92, 16, v216
	v_lshlrev_b32_e32 v93, 16, v217
	v_lshlrev_b32_e32 v95, 16, v218
	v_lshlrev_b32_e32 v85, 16, v219
	v_lshlrev_b32_e32 v89, 16, v220
	v_lshlrev_b32_e32 v87, 16, v221
	v_lshlrev_b32_e32 v91, 16, v222
	v_add_co_u32_e32 v0, vcc, s91, v74
	s_mov_b32 s0, 0x82000
	s_nop 0
	v_addc_co_u32_e32 v1, vcc, 0, v75, vcc
	v_add_co_u32_e32 v2, vcc, s0, v74
	s_add_u32 s0, s54, s6
	s_nop 0
	v_addc_co_u32_e32 v3, vcc, 0, v75, vcc
	v_add_co_u32_e32 v4, vcc, 0x84000, v74
	s_addc_u32 s1, s55, 0
	s_nop 0
	v_addc_co_u32_e32 v5, vcc, 0, v75, vcc
	v_add_co_u32_e32 v6, vcc, 0x86000, v74
	v_cmp_gt_u32_e64 s[26:27], 16, v40
	s_nop 0
	v_addc_co_u32_e32 v7, vcc, 0, v75, vcc
	global_load_ushort v100, v[0:1], off
	global_load_ushort v99, v[2:3], off
	global_load_ushort v61, v[4:5], off
	global_load_ushort v57, v[6:7], off
	v_lshl_add_u64 v[0:1], s[64:65], 0, v[40:41]
	v_lshlrev_b64 v[0:1], 8, v[0:1]
	v_cmp_lt_u32_e64 s[24:25], 31, v40
	v_cmp_lt_u32_e64 s[22:23], 47, v40
	v_lshlrev_b32_e32 v135, 2, v40
	v_lshl_add_u64 v[82:83], s[0:1], 0, v[0:1]
	s_and_saveexec_b64 s[0:1], s[4:5]
	s_cbranch_execz .LBB0_966
	v_add_co_u32_e32 v0, vcc, 0x8000, v82
	s_nop 1
	v_addc_co_u32_e32 v1, vcc, 0, v83, vcc
	global_load_dword v0, v[0:1], off
	v_mul_f32_e64 v1, v118, -v120
	s_nop 1
	v_mov_b32_dpp v1, v1 row_shr:1 row_mask:0xf bank_mask:0xf bound_ctrl:1
	v_fma_f32 v1, v118, -v120, v1
	s_nop 1
	v_add_f32_dpp v1, v1, v1 row_shr:2 row_mask:0xf bank_mask:0xf bound_ctrl:1
	s_nop 1
	v_add_f32_dpp v1, v1, v1 row_shr:4 row_mask:0xf bank_mask:0xf bound_ctrl:1
	s_nop 1
	v_add_f32_dpp v1, v1, v1 row_shr:8 row_mask:0xf bank_mask:0xf bound_ctrl:1
	s_nop 0
	v_readlane_b32 s3, v1, 15
	v_readlane_b32 s6, v1, 31
	v_readlane_b32 s7, v1, 47
	v_mov_b32_e32 v2, s3
	v_mov_b32_e32 v3, s6
	v_cndmask_b32_e64 v2, v2, 0, s[26:27]
	v_cndmask_b32_e64 v3, 0, v3, s[24:25]
	v_add_f32_e32 v2, v2, v3
	v_mov_b32_e32 v3, s7
	v_cndmask_b32_e64 v3, 0, v3, s[22:23]
	v_add_f32_e32 v2, v3, v2
	v_add_f32_e32 v1, v1, v2
	v_add_u32_e32 v2, 0x1e300, v135
	ds_write_b32 v2, v1
	v_add_u32_e32 v1, 0x1e600, v135
	ds_write_b32 v1, v118
	s_waitcnt vmcnt(0)
	v_mov_b32_e32 v118, v0

; template <int DUMMY>
; __device__ void ssd_item(const Params& p, int item) {
;     ...
;     if (c + 1 < 128) {
;       load_raw(c + 1);
;       const size_t zn = zbase + (size_t)64 * 4096;
; #pragma unroll
;       for (int r = 0; r < 4; ++r) znext[r] = zy[zn + (size_t)r * 4096];
;       if (wid == 0) {
;         float dt_use = dt_n;
;         if (c + 2 < 128) dt_n = dtb[(tb + (c + 2) * 64 + lane) * 64 + h];
;         write_cs(dt_use, nxt3);
;       }
.LBB0_1047:
	s_or_b64 exec, exec, s[30:31]
	v_lshl_add_u64 v[32:33], s[42:43], 0, v[84:85]
	v_add_co_u32_e32 v34, vcc, 0xb280000, v32
	s_add_i32 s30, s97, 1
	s_nop 0
	v_addc_co_u32_e32 v35, vcc, 0, v33, vcc
	global_load_ushort v170, v[34:35], off
	v_add_co_u32_e32 v34, vcc, 0xb282000, v32
	s_cmp_lg_u32 s97, 2
	s_nop 0
	v_addc_co_u32_e32 v35, vcc, 0, v33, vcc
	global_load_ushort v169, v[34:35], off
	v_add_co_u32_e32 v34, vcc, 0xb284000, v32
	s_cselect_b32 s97, s30, 0
	s_nop 0
	v_addc_co_u32_e32 v35, vcc, 0, v33, vcc
	v_add_co_u32_e32 v32, vcc, 0xb286000, v32
	global_load_ushort v168, v[34:35], off
	s_nop 0
	v_addc_co_u32_e32 v33, vcc, 0, v33, vcc
	global_load_ushort v49, v[32:33], off
	s_and_saveexec_b64 s[30:31], s[4:5]
	s_cbranch_execz .LBB0_1049
	v_lshl_add_u64 v[32:33], s[42:43], 0, v[92:93]
	global_load_dword v255, v[32:33], off
	v_mul_f32_e64 v33, v118, -v120
	s_nop 1
	v_mov_b32_dpp v33, v33 row_shr:1 row_mask:0xf bank_mask:0xf bound_ctrl:1
	v_fma_f32 v33, v118, -v120, v33
	s_nop 1
	v_add_f32_dpp v33, v33, v33 row_shr:2 row_mask:0xf bank_mask:0xf bound_ctrl:1
	s_nop 1
	v_add_f32_dpp v33, v33, v33 row_shr:4 row_mask:0xf bank_mask:0xf bound_ctrl:1
	s_nop 1
	v_add_f32_dpp v33, v33, v33 row_shr:8 row_mask:0xf bank_mask:0xf bound_ctrl:1
	s_nop 0
	v_readlane_b32 s72, v33, 15
	v_readlane_b32 s73, v33, 31
	v_readlane_b32 vcc_lo, v33, 47
	v_mov_b32_e32 v34, s72
	v_mov_b32_e32 v35, s73
	v_cndmask_b32_e64 v34, v34, 0, s[26:27]
	v_cndmask_b32_e64 v35, 0, v35, s[24:25]
	v_add_f32_e32 v34, v34, v35
	v_mov_b32_e32 v35, vcc_lo
	v_cndmask_b32_e64 v35, 0, v35, s[22:23]
	v_add_f32_e32 v34, v35, v34
	v_add_f32_e32 v33, v33, v34
	v_lshl_or_b32 v34, s97, 8, v135
	v_add_u32_e32 v35, 0x1e200, v34
	ds_write_b32 v35, v33
	v_add_u32_e32 v33, 0x1e500, v34
	ds_write_b32 v33, v118

; __device__ __forceinline__ float bf2f(u16 h) { return __uint_as_float(((unsigned)h) << 16); }
; __device__ __forceinline__ float siluf_(float v) { return v * __builtin_amdgcn_rcpf(1.f + __expf(-v)); }
; template <int DUMMY>
; __device__ void ssd_item(const Params& p, int item) {
;     ...
;     {
;       float dec = __expf(cs[63]);
; #pragma unroll
;       for (int j = 0; j < 2; ++j) {
;         accS[j][0] *= dec; accS[j][1] *= dec; accS[j][2] *= dec; accS[j][3] *= dec;
;       }
; #pragma unroll
;       for (int ks = 0; ks < 2; ++ks) {
;         bf16x8 a = *(const bf16x8*)(xwT + (pf * 16 + fr) * 72 + ks * 32 + g4 * 8);
; #pragma unroll
;         for (int j = 0; j < 2; ++j) {
;           bf16x8 bb = *(const bf16x8*)(BTs + ((nf0 + j) * 16 + fr) * 72 + ks * 32 + g4 * 8);
;           accS[j] = __builtin_amdgcn_mfma_f32_16x16x32_bf16(a, bb, accS[j], 0, 0, 0);
;         }
;       }
;     }
;     __builtin_amdgcn_s_setprio(0);
;     RAW_BARRIER();
;     __builtin_amdgcn_s_setprio(1);
;     {
;       f32x4 yd = {0.f, 0.f, 0.f, 0.f}, yo = {0.f, 0.f, 0.f, 0.f};
; #pragma unroll
;       for (int ks = 0; ks < 2; ++ks) {
;         bf16x8 a = *(const bf16x8*)(Gs + (lf * 16 + fr) * 72 + ks * 32 + g4 * 8);
;         bf16x8 bb = *(const bf16x8*)(xdT + (pf * 16 + fr) * 72 + ks * 32 + g4 * 8);
;         yd = __builtin_amdgcn_mfma_f32_16x16x32_bf16(a, bb, yd, 0, 0, 0);
;       }
; #pragma unroll
;       for (int ks = 0; ks < 4; ++ks) {
;         bf16x8 a = *(const bf16x8*)(Cs + (lf * 16 + fr) * 136 + ks * 32 + g4 * 8);
;         bf16x8 bb = *(const bf16x8*)(Sb + (pf * 16 + fr) * 136 + ks * 32 + g4 * 8);
;         yo = __builtin_amdgcn_mfma_f32_16x16x32_bf16(a, bb, yo, 0, 0, 0);
;       }
;       __builtin_amdgcn_s_setprio(0);
;       bf16x4 xs4 = *(const bf16x4*)(xT + (pf * 16 + fr) * 72 + lf * 16 + g4 * 4);
; #pragma unroll
;       for (int r = 0; r < 4; ++r) {
;         int l_ = lf * 16 + g4 * 4 + r;
;         float y = yd[r] + __expf(cs[l_]) * yo[r] + Dh * bf2f((u16)xs4[r]);
;         y *= siluf_(bf2f(zcur[r]));
;         ytile[l_ * 36 + pf * 16 + fr] = f2bf(y);
;         float sq = row16_sum(y * y);
;         if (fr == 0) sqs[wid * 16 + g4 * 4 + r] = sq;
;       }
.LBB0_1067:
	s_or_b64 exec, exec, s[30:31]
	v_mov_b32_e32 v33, s52
	ds_read_b32 v100, v33 offset:252
	ds_write_b16 v131, v32
	ds_read_b128 v[32:35], v134 offset:57856
	s_waitcnt lgkmcnt(7)
	ds_read_b128 v[36:39], v136 offset:34816
	ds_read_b128 v[178:181], v138 offset:34816
	ds_read_b128 v[182:185], v134 offset:57920
	ds_read_b128 v[186:189], v136 offset:34880
	s_waitcnt lgkmcnt(6)
	v_mul_f32_e32 v100, 0x3fb8aa3b, v100
	v_exp_f32_e32 v100, v100
	s_nop 0
	v_pk_mul_f32 v[6:7], v[6:7], v[100:101] op_sel_hi:[1,0]
	v_pk_mul_f32 v[4:5], v[4:5], v[100:101] op_sel_hi:[1,0]
	v_pk_mul_f32 v[2:3], v[2:3], v[100:101] op_sel_hi:[1,0]
	v_pk_mul_f32 v[0:1], v[0:1], v[100:101] op_sel_hi:[1,0]
	s_waitcnt lgkmcnt(3)
	v_mfma_f32_16x16x32_bf16 v[4:7], v[32:35], v[36:39], v[4:7]
	ds_read_b128 v[36:39], v138 offset:34880
	s_waitcnt lgkmcnt(3)
	v_mfma_f32_16x16x32_bf16 v[0:3], v[32:35], v[178:181], v[0:3]
	s_waitcnt lgkmcnt(1)
	v_mfma_f32_16x16x32_bf16 v[4:7], v[182:185], v[186:189], v[4:7]
	s_waitcnt lgkmcnt(0)
	v_mfma_f32_16x16x32_bf16 v[0:3], v[182:185], v[36:39], v[0:3]
	s_setprio 0
	s_waitcnt lgkmcnt(0)
	s_barrier
	s_setprio 1
	ds_read_b128 v[32:35], v42
	v_add3_u32 v100, s78, v162, v161
	ds_read_b128 v[36:39], v100
	ds_read_b128 v[178:181], v132
	ds_read_b128 v[182:185], v42 offset:64
	ds_read_b128 v[186:189], v100 offset:64
	v_add3_u32 v101, s53, v160, v161
	s_waitcnt lgkmcnt(3)
	v_mfma_f32_16x16x32_bf16 v[32:35], v[32:35], v[36:39], 0
	ds_read_b128 v[36:39], v101
	ds_read_b128 v[190:193], v132 offset:64
	ds_read_b128 v[194:197], v101 offset:64
	s_waitcnt lgkmcnt(2)
	v_mfma_f32_16x16x32_bf16 v[178:181], v[178:181], v[36:39], 0
	ds_read_b128 v[36:39], v42 offset:128
	ds_read_b128 v[198:201], v42 offset:192
	v_mfma_f32_16x16x32_bf16 v[32:35], v[182:185], v[186:189], v[32:35]
	ds_read_b128 v[182:185], v100 offset:128
	ds_read_b128 v[186:189], v100 offset:192
	s_waitcnt lgkmcnt(1)
	v_mfma_f32_16x16x32_bf16 v[32:35], v[36:39], v[182:185], v[32:35]
	s_waitcnt lgkmcnt(0)
	v_mfma_f32_16x16x32_bf16 v[36:39], v[198:201], v[186:189], v[32:35]
	v_mfma_f32_16x16x32_bf16 v[32:35], v[190:193], v[194:197], v[178:181]
	s_setprio 0
	v_add_u32_e32 v42, s77, v160
	v_add3_u32 v42, v42, v163, v164
	ds_read_b32 v177, v87
	ds_read_b64 v[100:101], v42
	s_waitcnt vmcnt(14)
	v_lshlrev_b32_e32 v42, 16, v167
	v_mul_f32_e32 v167, 0xbfb8aa3b, v42
	v_exp_f32_e32 v167, v167
	s_waitcnt lgkmcnt(1)
	v_mul_f32_e32 v177, 0x3fb8aa3b, v177
	v_exp_f32_e32 v177, v177
	v_add_f32_e32 v167, 1.0, v167
	v_rcp_f32_e32 v167, v167
	v_fma_f32 v32, v36, v177, v32
	s_waitcnt lgkmcnt(0)
	v_lshlrev_b32_e32 v36, 16, v100
	v_fmac_f32_e32 v32, v43, v36
	v_mul_f32_e32 v36, v167, v42
	v_mul_f32_e32 v32, v36, v32
	v_cvt_pk_bf16_f32 v36, v32, s0
	ds_write_b16 v123, v36
	v_mul_f32_e32 v36, v32, v32
	s_nop 1
	v_mov_b32_dpp v36, v36 quad_perm:[1,0,3,2] row_mask:0xf bank_mask:0xf bound_ctrl:1
	v_fmac_f32_e32 v36, v32, v32
	s_nop 1
	v_add_f32_dpp v32, v36, v36 quad_perm:[2,3,0,1] row_mask:0xf bank_mask:0xf bound_ctrl:1
	s_nop 1
	v_add_f32_dpp v32, v32, v32 row_half_mirror row_mask:0xf bank_mask:0xf bound_ctrl:1
	s_nop 1
	v_mov_b32_dpp v36, v32 row_mirror row_mask:0xf bank_mask:0xf bound_ctrl:1
	s_and_saveexec_b64 s[30:31], s[0:1]
	v_add_f32_e32 v32, v32, v36
	ds_write_b32 v122, v32
	s_or_b64 exec, exec, s[30:31]
	s_waitcnt vmcnt(13)
	v_lshlrev_b32_e32 v166, 16, v166
	ds_read_b32 v32, v87 offset:4
	v_mul_f32_e32 v36, 0xbfb8aa3b, v166
	v_exp_f32_e32 v36, v36
	v_and_b32_e32 v167, 0xffff0000, v100
	s_waitcnt lgkmcnt(0)
	v_mul_f32_e32 v32, 0x3fb8aa3b, v32
	v_add_f32_e32 v36, 1.0, v36
	v_exp_f32_e32 v32, v32
	v_rcp_f32_e32 v42, v36
	v_fma_f32 v36, v37, v32, v33
	v_pk_mul_f32 v[32:33], v[42:43], v[166:167]
	s_nop 0
	v_add_f32_e32 v33, v33, v36
	v_mul_f32_e32 v32, v32, v33
	v_cvt_pk_bf16_f32 v33, v32, s0
	v_mul_f32_e32 v36, v32, v32
	ds_write_b16 v123, v33 offset:72
	s_nop 0
	v_mov_b32_dpp v33, v36 quad_perm:[1,0,3,2] row_mask:0xf bank_mask:0xf bound_ctrl:1
	v_fmac_f32_e32 v33, v32, v32
	s_nop 1
	v_add_f32_dpp v32, v33, v33 quad_perm:[2,3,0,1] row_mask:0xf bank_mask:0xf bound_ctrl:1
	s_nop 1
	v_add_f32_dpp v32, v32, v32 row_half_mirror row_mask:0xf bank_mask:0xf bound_ctrl:1
	s_nop 1
	v_mov_b32_dpp v33, v32 row_mirror row_mask:0xf bank_mask:0xf bound_ctrl:1
	s_and_saveexec_b64 s[30:31], s[0:1]
	v_add_f32_e32 v32, v32, v33
	ds_write_b32 v122, v32 offset:4
	s_or_b64 exec, exec, s[30:31]
	ds_read_b32 v33, v87 offset:8
	s_waitcnt vmcnt(12)
	v_lshlrev_b32_e32 v32, 16, v165
	v_mul_f32_e32 v36, 0xbfb8aa3b, v32
	v_exp_f32_e32 v36, v36
	s_waitcnt lgkmcnt(0)
	v_mul_f32_e32 v33, 0x3fb8aa3b, v33
	v_exp_f32_e32 v37, v33
	v_add_f32_e32 v33, 1.0, v36
	v_rcp_f32_e32 v42, v33
	v_lshlrev_b32_e32 v33, 16, v101
	v_fma_f32 v34, v38, v37, v34
	v_pk_mul_f32 v[32:33], v[42:43], v[32:33]
	s_nop 0
	v_add_f32_e32 v33, v33, v34
	v_mul_f32_e32 v32, v32, v33
	v_cvt_pk_bf16_f32 v33, v32, s0
	v_mul_f32_e32 v34, v32, v32
	ds_write_b16 v123, v33 offset:144
	s_nop 0
	v_mov_b32_dpp v33, v34 quad_perm:[1,0,3,2] row_mask:0xf bank_mask:0xf bound_ctrl:1
	v_fmac_f32_e32 v33, v32, v32
	s_nop 1
	v_add_f32_dpp v32, v33, v33 quad_perm:[2,3,0,1] row_mask:0xf bank_mask:0xf bound_ctrl:1
	s_nop 1
	v_add_f32_dpp v32, v32, v32 row_half_mirror row_mask:0xf bank_mask:0xf bound_ctrl:1
	s_nop 1
	v_mov_b32_dpp v33, v32 row_mirror row_mask:0xf bank_mask:0xf bound_ctrl:1
	s_and_saveexec_b64 s[30:31], s[0:1]
	v_add_f32_e32 v32, v32, v33
	ds_write_b32 v122, v32 offset:8
	s_or_b64 exec, exec, s[30:31]
	ds_read_b32 v33, v87 offset:12
	s_waitcnt vmcnt(11)
	v_lshlrev_b32_e32 v32, 16, v75
	v_mul_f32_e32 v34, 0xbfb8aa3b, v32
	v_exp_f32_e32 v34, v34
	s_waitcnt lgkmcnt(0)
; template <int DUMMY>
; __device__ void ssd_item(const Params& p, int item) {
;     ...
;     for (int r = 0; r < 4; ++r) zcur[r] = znext[r];
;     if (c > 1) {
;       const size_t yi = (tb + (c - 2) * 64 + (tid >> 3)) * 4096 + h * 64 + ph * 32 + (tid & 7) * 4;
;       *(i32x2*)(zyo + (yi & omask)) = ypend;
;     }
;     if (c + 1 < 128) {
;       load_raw(c + 1);
;       const size_t zn = zbase + (size_t)64 * 4096;
; #pragma unroll
;       for (int r = 0; r < 4; ++r) znext[r] = zy[zn + (size_t)r * 4096];
	v_mul_f32_e32 v33, 0x3fb8aa3b, v33
	v_exp_f32_e32 v36, v33
	v_add_f32_e32 v33, 1.0, v34
	v_rcp_f32_e32 v42, v33
	v_and_b32_e32 v33, 0xffff0000, v101
	v_fmac_f32_e32 v35, v39, v36
	v_pk_mul_f32 v[32:33], v[42:43], v[32:33]
	s_nop 0
	v_add_f32_e32 v33, v33, v35
	v_mul_f32_e32 v32, v32, v33
	v_cvt_pk_bf16_f32 v33, v32, s0
	v_mul_f32_e32 v34, v32, v32
	ds_write_b16 v123, v33 offset:216
	s_nop 0
	v_mov_b32_dpp v33, v34 quad_perm:[1,0,3,2] row_mask:0xf bank_mask:0xf bound_ctrl:1
	v_fmac_f32_e32 v33, v32, v32
	s_nop 1
	v_add_f32_dpp v32, v33, v33 quad_perm:[2,3,0,1] row_mask:0xf bank_mask:0xf bound_ctrl:1
	s_nop 1
	v_add_f32_dpp v32, v32, v32 row_half_mirror row_mask:0xf bank_mask:0xf bound_ctrl:1
	s_nop 1
	v_mov_b32_dpp v33, v32 row_mirror row_mask:0xf bank_mask:0xf bound_ctrl:1
	s_and_saveexec_b64 s[30:31], s[0:1]
	v_add_f32_e32 v32, v32, v33
	ds_write_b32 v122, v32 offset:12
	s_or_b64 exec, exec, s[30:31]
	s_add_u32 s70, s70, 0x40000
	s_addc_u32 s71, s71, 0
	s_mov_b64 s[30:31], 0x4000
	s_add_i32 s76, s76, 1
	s_waitcnt vmcnt(4)
	v_perm_b32 v42, v40, v176, s94
	v_perm_b32 v100, v176, v175, s94
	v_perm_b32 v101, v175, v173, s94
	v_perm_b32 v173, v173, v174, s94
	v_perm_b32 v171, v172, v171, s94
	v_lshl_add_u64 v[84:85], v[84:85], 0, s[60:61]
	v_add_u32_e32 v86, 64, v86
	v_lshl_add_u64 v[92:93], v[92:93], 0, s[30:31]
	v_lshl_add_u64 v[94:95], v[94:95], 0, s[62:63]
	v_lshl_add_u64 v[96:97], v[96:97], 0, s[62:63]
	s_cmp_eq_u32 s70, 0x1f00000
	v_lshl_add_u64 v[98:99], v[98:99], 0, s[60:61]
	s_waitcnt vmcnt(0)
	v_mov_b32_e32 v118, v255
	s_cbranch_scc1 .LBB0_1077
	s_waitcnt vmcnt(0)
	v_mov_b32_e32 v75, v49
	v_mov_b32_e32 v165, v168
	v_mov_b32_e32 v166, v169
	v_mov_b32_e32 v167, v170
	v_lshl_add_u64 v[224:225], v[78:79], 0, s[70:71]
	v_lshl_add_u64 v[226:227], v[80:81], 0, s[70:71]
	v_add_co_u32_e32 v224, vcc, 0x100000, v224
	s_nop 1
	v_addc_co_u32_e32 v225, vcc, 0, v225, vcc
	v_add_co_u32_e32 v226, vcc, 0x100000, v226
	s_nop 1
	v_addc_co_u32_e32 v227, vcc, 0, v227, vcc
	global_load_dword v228, v[224:225], off
	global_load_dword v228, v[224:225], off offset:2048
	global_load_dword v228, v[226:227], off
	global_load_dword v228, v[226:227], off offset:2048
	v_add_u32_e32 v224, 61, v86
	v_mov_b32_e32 v225, v41
	v_lshl_add_u64 v[224:225], s[64:65], 0, v[224:225]
	v_mad_u64_u32 v[226:227], s[72:73], v224, s86, v[66:67]
	v_mad_i32_i24 v227, v225, s86, v227
	global_load_ushort v228, v[226:227], off
	v_add_co_u32_e32 v226, vcc, 0x3000, v226
	s_nop 1
	v_addc_co_u32_e32 v227, vcc, 0, v227, vcc
	global_load_ushort v228, v[226:227], off
	v_add_co_u32_e32 v226, vcc, 0x3000, v226
	s_nop 1
	v_addc_co_u32_e32 v227, vcc, 0, v227, vcc
	global_load_ushort v228, v[226:227], off
	v_add_co_u32_e32 v226, vcc, 0x3000, v226
	s_nop 1
	v_addc_co_u32_e32 v227, vcc, 0, v227, vcc
	global_load_ushort v228, v[226:227], off
	v_lshl_add_u64 v[224:225], v[84:85], 0, s[60:61]
	v_lshl_add_u64 v[224:225], s[42:43], 0, v[224:225]
	v_add_co_u32_e32 v226, vcc, 0xb280000, v224
	s_nop 1
	v_addc_co_u32_e32 v227, vcc, 0, v225, vcc
	global_load_ushort v228, v[226:227], off
	v_add_co_u32_e32 v226, vcc, 0xb282000, v224
	s_nop 1
	v_addc_co_u32_e32 v227, vcc, 0, v225, vcc
	global_load_ushort v228, v[226:227], off
	v_add_co_u32_e32 v226, vcc, 0xb284000, v224
	s_nop 1
	v_addc_co_u32_e32 v227, vcc, 0, v225, vcc
	global_load_ushort v228, v[226:227], off
	v_add_co_u32_e32 v226, vcc, 0xb286000, v224
	s_nop 1
	v_addc_co_u32_e32 v227, vcc, 0, v225, vcc
	global_load_ushort v228, v[226:227], off
	s_branch .LBB0_1033
.LBB0_1077:
	s_lshl_b32 s3, s97, 8
	v_mov_b32_e32 v75, v41
	s_add_i32 s52, s3, 0x1e200
	v_lshl_add_u64 v[32:33], s[48:49], 0, v[74:75]
	s_lshl_b32 s72, s75, 1
	s_mov_b32 s73, s59
	ds_write_b128 v116, v[20:23] offset:17408
	ds_write_b128 v116, v[16:19]
	ds_write_b16 v52, v12 offset:34816
	ds_write_b16_d16_hi v52, v12 offset:34960
	ds_write_b16 v52, v13 offset:35104
	ds_write_b16_d16_hi v52, v13 offset:35248
	ds_write_b16 v52, v14 offset:35392
	ds_write_b16_d16_hi v52, v14 offset:35536
	ds_write_b16 v52, v15 offset:35680
	ds_write_b16_d16_hi v52, v15 offset:35824
	ds_write_b128 v117, v[24:27] offset:17408
	ds_write_b128 v117, v[28:31]
	ds_write_b16 v54, v8 offset:34816
	ds_write_b16_d16_hi v54, v8 offset:34960
	ds_write_b16 v54, v9 offset:35104
	ds_write_b16_d16_hi v54, v9 offset:35248
	ds_write_b16 v54, v10 offset:35392
	ds_write_b16_d16_hi v54, v10 offset:35536
	ds_write_b16 v54, v11 offset:35680
	ds_write_b16_d16_hi v54, v11 offset:35824
	v_mov_b32_e32 v8, s52
	v_lshl_add_u64 v[32:33], v[32:33], 0, s[72:73]
	s_lshl_b32 s74, s74, 1
	s_mov_b32 s75, s59
	ds_read_b32 v55, v8 offset:252
	v_lshl_add_u32 v8, v50, 2, s52
	v_lshl_add_u64 v[80:81], v[32:33], 0, s[74:75]
	ds_read2_b32 v[38:39], v115 offset1:32
	ds_read_b128 v[30:33], v8
	ds_read2_b32 v[84:85], v115 offset0:64 offset1:96
	v_add_u32_e32 v8, s3, v114
	ds_read_b32 v40, v115 offset:512
	ds_read_b128 v[34:37], v8
	v_lshl_add_u64 v[78:79], s[64:65], 0, v[44:45]
	s_waitcnt lgkmcnt(3)
; __device__ __forceinline__ float bf2f(u16 h) { return __uint_as_float(((unsigned)h) << 16); }
; __device__ __forceinline__ float siluf_(float v) { return v * __builtin_amdgcn_rcpf(1.f + __expf(-v)); }
; template <int DUMMY>
; __device__ void ssd_item(const Params& p, int item) {
;     ...
; #pragma unroll
;     for (int i = 0; i < 7; ++i) {
;       int row = c * 64 + l0 - 3 + i;
;       rX[i] = row >= 0 ? xbc[(tb + row) * 6144 + colX + chg] : (u16)0;
;     }
;     ...
;         float w0 = cwX[0 * 32 + chg], w1 = cwX[1 * 32 + chg], w2 = cwX[2 * 32 + chg], w3 = cwX[3 * 32 + chg], bx = cwX[4 * 32 + chg];
;         float raw[7];
; #pragma unroll
;         for (int i = 0; i < 7; ++i) raw[i] = bf2f(rX[i]);
;         const float cs63 = cs[63];
;         float4 dt4 = *(const float4*)(dv + l0), cs4 = *(const float4*)(cs + l0);
;         float dts[4] = {dt4.x, dt4.y, dt4.z, dt4.w}, css[4] = {cs4.x, cs4.y, cs4.z, cs4.w};
;         float vx[4], vd[4], vw[4];
; #pragma unroll
;         for (int j = 0; j < 4; ++j) {
;           float s = bx + w0 * raw[j] + w1 * raw[j + 1] + w2 * raw[j + 2] + w3 * raw[j + 3];
;           vx[j] = siluf_(s);
;           vd[j] = vx[j] * dts[j];
;           vw[j] = vd[j] * __expf(cs63 - css[j]);
;         }
;         *(i32x2*)(xT + chg * 72 + l0) = i32x2{(int)pack2(vx[0], vx[1]), (int)pack2(vx[2], vx[3])};
;         *(i32x2*)(xdT + chg * 72 + l0) = i32x2{(int)pack2(vd[0], vd[1]), (int)pack2(vd[2], vd[3])};
;         *(i32x2*)(xwT + chg * 72 + l0) = i32x2{(int)pack2(vw[0], vw[1]), (int)pack2(vw[2], vw[3])};
;       }
;     }
; #pragma unroll
;     for (int j = 0; j < 2; ++j)
; #pragma unroll
;       for (int r = 0; r < 4; ++r) Sb[(pf * 16 + g4 * 4 + r) * 136 + (nf0 + j) * 16 + fr] = f2bf(accS[j][r]);
; #pragma unroll
;     for (int r = 0; r < 4; ++r) zcur[r] = znext[r];
;     if (c > 1) {
;       const size_t yi = (tb + (c - 2) * 64 + (tid >> 3)) * 4096 + h * 64 + ph * 32 + (tid & 7) * 4;
;       *(i32x2*)(zyo + (yi & omask)) = ypend;
;     }
	v_sub_f32_e32 v8, v55, v30
	v_mul_f32_e32 v8, 0x3fb8aa3b, v8
	v_exp_f32_e32 v86, v8
	v_sub_f32_e32 v8, v55, v31
	v_mul_f32_e32 v8, 0x3fb8aa3b, v8
	v_exp_f32_e32 v87, v8
	v_sub_f32_e32 v8, v55, v32
	v_lshlrev_b64 v[78:79], 13, v[78:79]
	v_mul_f32_e32 v8, 0x3fb8aa3b, v8
	v_lshl_add_u64 v[80:81], v[80:81], 0, v[78:79]
	s_mov_b32 s3, 0x3e00000
	v_exp_f32_e32 v32, v8
	v_add_co_u32_e32 v8, vcc, s3, v80
	s_mov_b32 s3, 0x1fc0000
	s_nop 0
	v_addc_co_u32_e32 v9, vcc, 0, v81, vcc
	v_add_co_u32_e32 v12, vcc, s3, v68
	s_mov_b64 s[30:31], 0x1fc0000
	s_nop 0
	v_addc_co_u32_e32 v13, vcc, 0, v69, vcc
	v_lshl_add_u64 v[20:21], v[72:73], 0, s[30:31]
	v_add_co_u32_e32 v22, vcc, 0x1fc0000, v70
	global_store_dwordx2 v[8:9], v[82:83], off
	v_lshl_add_u64 v[16:17], v[62:63], 1, v[20:21]
	v_addc_co_u32_e32 v23, vcc, 0, v71, vcc
	v_lshl_add_u64 v[20:21], v[64:65], 1, v[20:21]
	global_load_dwordx4 v[8:11], v[12:13], off
	s_nop 0
	global_load_dwordx4 v[12:15], v[12:13], off offset:2048
	s_nop 0
	global_load_dwordx4 v[16:19], v[16:17], off
	s_nop 0
	global_load_dwordx4 v[24:27], v[22:23], off
	global_load_dwordx4 v[28:31], v[22:23], off offset:2048
	s_nop 0
	global_load_dwordx4 v[20:23], v[20:21], off
	v_and_b32_e32 v69, 0xffff0000, v171
	v_lshlrev_b32_e32 v68, 16, v171
	v_and_b32_e32 v89, 0xffff0000, v173
	v_lshlrev_b32_e32 v88, 16, v173
	s_waitcnt lgkmcnt(1)
	v_pk_fma_f32 v[70:71], v[38:39], v[68:69], v[40:41] op_sel_hi:[0,1,0]
	v_mov_b32_e32 v68, v39
	v_lshlrev_b32_e32 v62, 16, v101
	v_pk_mov_b32 v[72:73], v[68:69], v[88:89] op_sel:[1,0]
	v_lshlrev_b32_e32 v64, 16, v100
	v_pk_fma_f32 v[70:71], v[68:69], v[72:73], v[70:71] op_sel_hi:[0,1,1]
	v_mov_b32_e32 v72, v88
	v_mov_b32_e32 v73, v62
	v_pk_fma_f32 v[70:71], v[84:85], v[72:73], v[70:71] op_sel_hi:[0,1,1]
	v_mov_b32_e32 v72, v85
	v_mov_b32_e32 v82, v62
	v_mov_b32_e32 v83, v64
	v_pk_fma_f32 v[70:71], v[72:73], v[82:83], v[70:71] op_sel_hi:[0,1,1]
	v_mul_f32_e32 v39, 0xbfb8aa3b, v70
	v_exp_f32_e32 v39, v39
	v_mul_f32_e32 v59, 0xbfb8aa3b, v71
	v_exp_f32_e32 v59, v59
	v_and_b32_e32 v63, 0xffff0000, v101
	v_add_f32_e32 v39, 1.0, v39
	v_rcp_f32_e32 v82, v39
	v_add_f32_e32 v39, 1.0, v59
	v_rcp_f32_e32 v83, v39
	v_pk_fma_f32 v[38:39], v[38:39], v[88:89], v[40:41] op_sel_hi:[0,1,0]
	v_and_b32_e32 v65, 0xffff0000, v100
	v_pk_fma_f32 v[38:39], v[68:69], v[62:63], v[38:39] op_sel_hi:[0,1,1]
	v_and_b32_e32 v91, 0xffff0000, v42
	v_lshlrev_b32_e32 v90, 16, v42
	v_pk_fma_f32 v[38:39], v[84:85], v[64:65], v[38:39] op_sel_hi:[0,1,1]
	v_pk_fma_f32 v[38:39], v[72:73], v[90:91], v[38:39] op_sel_hi:[0,1,1]
	v_mul_f32_e32 v40, 0xbfb8aa3b, v38
	v_exp_f32_e32 v40, v40
	v_mul_f32_e32 v42, 0xbfb8aa3b, v39
	v_exp_f32_e32 v42, v42
	v_sub_f32_e32 v33, v55, v33
	v_add_f32_e32 v40, 1.0, v40
	v_rcp_f32_e32 v62, v40
	v_add_f32_e32 v40, 1.0, v42
	v_rcp_f32_e32 v63, v40
	v_mul_f32_e32 v33, 0x3fb8aa3b, v33
	v_exp_f32_e32 v33, v33
	v_pk_mul_f32 v[70:71], v[70:71], v[82:83]
	v_pk_mul_f32 v[38:39], v[38:39], v[62:63]
	s_waitcnt lgkmcnt(0)
	v_pk_mul_f32 v[34:35], v[34:35], v[70:71]
	v_pk_mul_f32 v[36:37], v[36:37], v[38:39]
	v_pk_mul_f32 v[64:65], v[86:87], v[34:35]
	v_pk_mul_f32 v[32:33], v[36:37], v[32:33]
	v_cvt_pk_bf16_f32 v62, v70, v71
	v_cvt_pk_bf16_f32 v63, v38, v39
	v_cvt_pk_bf16_f32 v34, v34, v35
	v_cvt_pk_bf16_f32 v35, v36, v37
	v_cvt_pk_bf16_f32 v36, v64, v65
	v_cvt_pk_bf16_f32 v37, v32, v33
	v_cvt_pk_bf16_f32 v32, v4, s0
	v_add_u32_e32 v33, v53, v159
	ds_write_b64 v113, v[62:63] offset:62464
	ds_write2st64_b64 v113, v[34:35], v[36:37] offset0:104 offset1:113
	ds_write_b16 v33, v32
	v_cvt_pk_bf16_f32 v32, v5, s0
	ds_write_b16 v33, v32 offset:272
	v_cvt_pk_bf16_f32 v32, v6, s0
	ds_write_b16 v33, v32 offset:544
	v_cvt_pk_bf16_f32 v32, v7, s0
	ds_write_b16 v33, v32 offset:816
	v_cvt_pk_bf16_f32 v32, v0, s0
	v_add_u32_e32 v33, v51, v159
	ds_write_b16 v33, v32
	v_cvt_pk_bf16_f32 v32, v1, s0
	ds_write_b16 v33, v32 offset:272
	v_cvt_pk_bf16_f32 v32, v2, s0
	s_movk_i32 s3, 0xe042
	ds_write_b16 v33, v32 offset:544
	v_cvt_pk_bf16_f32 v32, v3, s0
	v_add_u32_e32 v40, 0x1fbd, v50
	v_cmp_lt_i32_e32 vcc, s3, v50
	v_mov_b32_e32 v63, 0
	v_mov_b32_e32 v62, 0
	ds_write_b16 v33, v32 offset:816
	v_mov_b32_e32 v216, 0
	v_mov_b32_e32 v217, 0
	v_mov_b32_e32 v218, 0
	v_mov_b32_e32 v219, 0
	v_mov_b32_e32 v220, 0
	v_mov_b32_e32 v221, 0
	v_mov_b32_e32 v222, 0
	s_and_saveexec_b64 s[30:31], vcc
	s_cbranch_execz .LBB0_1079
	v_lshl_add_u64 v[32:33], s[64:65], 0, v[40:41]
	v_mad_u64_u32 v[34:35], s[76:77], v32, s86, v[66:67]
	v_mad_i32_i24 v35, v33, s86, v35
	global_load_ushort v216, v[34:35], off
; template <int DUMMY>
; __device__ void ssd_item(const Params& p, int item) {
;     ...
; #pragma unroll
;     for (int i = 0; i < 7; ++i) {
;       int row = c * 64 + l0 - 3 + i;
;       rX[i] = row >= 0 ? xbc[(tb + row) * 6144 + colX + chg] : (u16)0;
;     }
;     ...
;     if (c + 1 < 128) {
;       load_raw(c + 1);
;       const size_t zn = zbase + (size_t)64 * 4096;
; #pragma unroll
;       for (int r = 0; r < 4; ++r) znext[r] = zy[zn + (size_t)r * 4096];
;       if (wid == 0) {
;         float dt_use = dt_n;
;         if (c + 2 < 128) dt_n = dtb[(tb + (c + 2) * 64 + lane) * 64 + h];
;         write_cs(dt_use, nxt3);
;       }
.LBB0_1079:
	s_or_b64 exec, exec, s[30:31]
	s_movk_i32 s3, 0xe041
	v_cmp_lt_i32_e64 s[30:31], s3, v50
	s_and_saveexec_b64 s[76:77], s[30:31]
	s_cbranch_execz .LBB0_1081
	v_add_u32_e32 v32, 0x1fbe, v50
	v_mov_b32_e32 v33, v41
	v_lshl_add_u64 v[32:33], s[64:65], 0, v[32:33]
	v_mad_u64_u32 v[34:35], s[30:31], v32, s86, v[66:67]
	v_mad_i32_i24 v35, v33, s86, v35
	global_load_ushort v217, v[34:35], off
.LBB0_1081:
	s_or_b64 exec, exec, s[76:77]
	v_mov_b32_e32 v51, 0
	v_mov_b32_e32 v53, 0
	s_and_saveexec_b64 s[30:31], vcc
	s_cbranch_execz .LBB0_1083
	v_or_b32_e32 v40, 2, v40
	v_lshl_add_u64 v[32:33], s[64:65], 0, v[40:41]
	v_mad_u64_u32 v[34:35], s[76:77], v32, s86, v[66:67]
	v_mad_i32_i24 v35, v33, s86, v35
	global_load_ushort v218, v[34:35], off
.LBB0_1083:
	s_or_b64 exec, exec, s[30:31]
	s_movk_i32 s3, 0xe03f
	v_cmp_lt_i32_e32 vcc, s3, v50
	s_and_saveexec_b64 s[30:31], vcc
	s_cbranch_execz .LBB0_1085
	v_add_u32_e32 v40, 0x1fc0, v50
	v_lshl_add_u64 v[32:33], s[64:65], 0, v[40:41]
	v_mad_u64_u32 v[34:35], s[76:77], v32, s86, v[66:67]
	v_mad_i32_i24 v35, v33, s86, v35
	global_load_ushort v219, v[34:35], off
.LBB0_1085:
	s_or_b64 exec, exec, s[30:31]
	s_movk_i32 s3, 0xe03e
	v_cmp_lt_i32_e32 vcc, s3, v50
	v_mov_b32_e32 v55, 0
	v_mov_b32_e32 v59, 0
	s_and_saveexec_b64 s[30:31], vcc
	s_cbranch_execz .LBB0_1087
	v_add_u32_e32 v40, 0x1fc1, v50
	v_lshl_add_u64 v[32:33], s[64:65], 0, v[40:41]
	v_mad_u64_u32 v[34:35], s[76:77], v32, s86, v[66:67]
	v_mad_i32_i24 v35, v33, s86, v35
	global_load_ushort v220, v[34:35], off
.LBB0_1087:
	s_or_b64 exec, exec, s[30:31]
	s_movk_i32 s3, 0xe03d
	v_cmp_lt_i32_e32 vcc, s3, v50
	s_and_saveexec_b64 s[30:31], vcc
	s_cbranch_execz .LBB0_1089
	v_add_u32_e32 v40, 0x1fc2, v50
	v_lshl_add_u64 v[32:33], s[64:65], 0, v[40:41]
	v_mad_u64_u32 v[34:35], s[76:77], v32, s86, v[66:67]
	v_mad_i32_i24 v35, v33, s86, v35
	global_load_ushort v221, v[34:35], off
.LBB0_1089:
	s_or_b64 exec, exec, s[30:31]
	s_movk_i32 s3, 0xe03c
	v_cmp_lt_i32_e32 vcc, s3, v50
	v_mov_b32_e32 v65, 0
	s_and_saveexec_b64 s[30:31], vcc
	s_cbranch_execz .LBB0_1091
	v_add_u32_e32 v40, 0x1fc3, v50
	v_lshl_add_u64 v[32:33], s[64:65], 0, v[40:41]
	v_mad_u64_u32 v[34:35], s[76:77], v32, s86, v[66:67]
	v_mad_i32_i24 v35, v33, s86, v35
	global_load_ushort v222, v[34:35], off
.LBB0_1091:
	s_or_b64 exec, exec, s[30:31]
	s_waitcnt vmcnt(0)
	v_lshlrev_b32_e32 v62, 16, v216
	v_lshlrev_b32_e32 v63, 16, v217
	v_lshlrev_b32_e32 v53, 16, v218
	v_lshlrev_b32_e32 v51, 16, v219
	v_lshlrev_b32_e32 v59, 16, v220
	v_lshlrev_b32_e32 v55, 16, v221
	v_lshlrev_b32_e32 v65, 16, v222
	v_lshlrev_b32_e32 v40, 14, v58
	s_lshl_b32 s3, s58, 5
	v_lshl_add_u64 v[32:33], s[68:69], 0, v[40:41]
	v_lshlrev_b64 v[34:35], 12, v[46:47]
	s_lshl_b32 s30, s96, 6
	v_lshl_add_u64 v[32:33], v[32:33], 0, v[34:35]
	s_or_b32 s58, s3, s30
	v_lshl_add_u64 v[32:33], s[58:59], 0, v[32:33]
	v_lshl_add_u64 v[32:33], v[32:33], 0, v[60:61]
	v_lshl_add_u64 v[32:33], v[32:33], 0, v[56:57]
	v_lshl_add_u64 v[32:33], v[32:33], 0, s[70:71]
	v_lshl_add_u64 v[32:33], v[32:33], 1, s[48:49]
	s_mov_b32 s3, 0x180000
	v_add_co_u32_e32 v34, vcc, s3, v32
	s_add_i32 s3, s97, 1
	s_nop 0
	v_addc_co_u32_e32 v35, vcc, 0, v33, vcc
	v_add_co_u32_e32 v36, vcc, 0x182000, v32
	s_cmp_lg_u32 s97, 2
	s_nop 0
	v_addc_co_u32_e32 v37, vcc, 0, v33, vcc
	v_add_co_u32_e32 v38, vcc, 0x184000, v32
	s_cselect_b32 s3, s3, 0
	s_nop 0
	v_addc_co_u32_e32 v39, vcc, 0, v33, vcc
	v_add_co_u32_e32 v32, vcc, 0x186000, v32
	s_nop 1
	v_addc_co_u32_e32 v33, vcc, 0, v33, vcc
	global_load_ushort v68, v[34:35], off
	global_load_ushort v67, v[36:37], off
	global_load_ushort v66, v[38:39], off
	global_load_ushort v40, v[32:33], off
	s_and_saveexec_b64 s[30:31], s[4:5]
	s_cbranch_execz .LBB0_1093
	v_mul_f32_e64 v32, v118, -v120
	s_nop 1
	v_mov_b32_dpp v32, v32 row_shr:1 row_mask:0xf bank_mask:0xf bound_ctrl:1
	v_fma_f32 v32, v118, -v120, v32
	s_nop 1
	v_add_f32_dpp v32, v32, v32 row_shr:2 row_mask:0xf bank_mask:0xf bound_ctrl:1
	s_nop 1
	v_add_f32_dpp v32, v32, v32 row_shr:4 row_mask:0xf bank_mask:0xf bound_ctrl:1
	s_nop 1
	v_add_f32_dpp v32, v32, v32 row_shr:8 row_mask:0xf bank_mask:0xf bound_ctrl:1
	s_nop 0
	v_readlane_b32 s4, v32, 15
	v_readlane_b32 s5, v32, 31
	v_readlane_b32 s53, v32, 47
	v_mov_b32_e32 v33, s4
	v_mov_b32_e32 v34, s5
	v_cndmask_b32_e64 v33, v33, 0, s[26:27]
	v_cndmask_b32_e64 v34, 0, v34, s[24:25]
	v_add_f32_e32 v33, v33, v34
	v_mov_b32_e32 v34, s53
	v_cndmask_b32_e64 v34, 0, v34, s[22:23]
	v_add_f32_e32 v33, v34, v33
	v_add_f32_e32 v32, v32, v33
	v_lshl_or_b32 v33, s3, 8, v135
	v_add_u32_e32 v34, 0x1e200, v33
	ds_write_b32 v34, v32
	v_add_u32_e32 v32, 0x1e500, v33
	ds_write_b32 v32, v118

; __global__ void __launch_bounds__(NT) fwd_megakernel(Params pk) {
;   cg::grid_group grid = cg::this_grid();
;   Params* gp = (Params*)(pk.ws + OFF_PARAMS) + blockIdx.x;
;   if (threadIdx.x == 0) *gp = pk;
;   __syncthreads();
;   const Params& p = *gp;
;   xcd_barrier_register((unsigned*)(pk.ws + OFF_BAR));
;     ...
;   run_phase<0>(p); flat_barrier((unsigned*)(gp->ws + OFF_BAR));
;     ...
;   run_phase<0>(p);
;   if (pk.ws == nullptr) grid.sync();
;   flat_barrier((unsigned*)(gp->ws + OFF_BAR));
;   run_phase<1>(p); flat_barrier((unsigned*)(gp->ws + OFF_BAR));
;     ...
;   run_phase<102>(p); flat_barrier((unsigned*)(gp->ws + OFF_BAR));
;     ...
;   run_phase<2>(p); flat_barrier((unsigned*)(gp->ws + OFF_BAR));
;   run_phase<3>(p); flat_barrier((unsigned*)(gp->ws + OFF_BAR));
;   run_phase<13>(p); flat_barrier((unsigned*)(gp->ws + OFF_BAR));
;     ...
;   run_phase<104>(p); flat_barrier((unsigned*)(gp->ws + OFF_BAR));
;     ...
;   run_phase<4>(p); flat_barrier((unsigned*)(gp->ws + OFF_BAR));
;   run_phase<5>(p); flat_barrier((unsigned*)(gp->ws + OFF_BAR));
;   run_phase<6>(p); flat_barrier((unsigned*)(gp->ws + OFF_BAR));
;   run_phase<7>(p); flat_barrier((unsigned*)(gp->ws + OFF_BAR));
;     ...
;   run_phase<8>(p); flat_barrier((unsigned*)(gp->ws + OFF_BAR));
;     ...
;   run_phase<8>(p); flat_barrier((unsigned*)(gp->ws + OFF_BAR));
;   run_phase<9>(p); flat_barrier((unsigned*)(gp->ws + OFF_BAR));
;     ...
;   run_phase<10>(p); flat_barrier((unsigned*)(gp->ws + OFF_BAR));
;     ...
;   run_phase<10>(p); flat_barrier((unsigned*)(gp->ws + OFF_BAR));
;   run_phase<11>(p); flat_barrier((unsigned*)(gp->ws + OFF_BAR));
;   run_phase<12>(p);
; }
	.amdhsa_kernel _Z14fwd_megakernel6Params
		.amdhsa_group_segment_fixed_size 131072
		.amdhsa_private_segment_fixed_size 0
		.amdhsa_kernarg_size 424
		.amdhsa_user_sgpr_count 2
		.amdhsa_user_sgpr_dispatch_ptr 0
		.amdhsa_user_sgpr_queue_ptr 0
		.amdhsa_user_sgpr_kernarg_segment_ptr 1
		.amdhsa_user_sgpr_dispatch_id 0
		.amdhsa_user_sgpr_kernarg_preload_length 0
		.amdhsa_user_sgpr_kernarg_preload_offset 0
		.amdhsa_user_sgpr_private_segment_size 0
		.amdhsa_uses_dynamic_stack 0
		.amdhsa_enable_private_segment 0
		.amdhsa_system_sgpr_workgroup_id_x 1
		.amdhsa_system_sgpr_workgroup_id_y 0
		.amdhsa_system_sgpr_workgroup_id_z 0
		.amdhsa_system_sgpr_workgroup_info 0
		.amdhsa_system_vgpr_workitem_id 2
		.amdhsa_next_free_vgpr 256
		.amdhsa_next_free_sgpr 98
		.amdhsa_accum_offset 256
		.amdhsa_reserve_vcc 1
		.amdhsa_float_round_mode_32 0
		.amdhsa_float_round_mode_16_64 0
		.amdhsa_float_denorm_mode_32 3
		.amdhsa_float_denorm_mode_16_64 3
		.amdhsa_dx10_clamp 1
		.amdhsa_ieee_mode 1
		.amdhsa_fp16_overflow 0
		.amdhsa_tg_split 0
		.amdhsa_exception_fp_ieee_invalid_op 0
		.amdhsa_exception_fp_denorm_src 0
		.amdhsa_exception_fp_ieee_div_zero 0
		.amdhsa_exception_fp_ieee_overflow 0
		.amdhsa_exception_fp_ieee_underflow 0
		.amdhsa_exception_fp_ieee_inexact 0
		.amdhsa_exception_int_div_zero 0
	.end_amdhsa_kernel

; __global__ void __launch_bounds__(NT) fwd_megakernel(Params pk) {
;   cg::grid_group grid = cg::this_grid();
;   Params* gp = (Params*)(pk.ws + OFF_PARAMS) + blockIdx.x;
;   if (threadIdx.x == 0) *gp = pk;
;   __syncthreads();
;   const Params& p = *gp;
;   xcd_barrier_register((unsigned*)(pk.ws + OFF_BAR));
;     ...
;   run_phase<0>(p); flat_barrier((unsigned*)(gp->ws + OFF_BAR));
;     ...
;   run_phase<0>(p);
;   if (pk.ws == nullptr) grid.sync();
;   flat_barrier((unsigned*)(gp->ws + OFF_BAR));
;   run_phase<1>(p); flat_barrier((unsigned*)(gp->ws + OFF_BAR));
;     ...
;   run_phase<102>(p); flat_barrier((unsigned*)(gp->ws + OFF_BAR));
;     ...
;   run_phase<2>(p); flat_barrier((unsigned*)(gp->ws + OFF_BAR));
;   run_phase<3>(p); flat_barrier((unsigned*)(gp->ws + OFF_BAR));
;   run_phase<13>(p); flat_barrier((unsigned*)(gp->ws + OFF_BAR));
;     ...
;   run_phase<104>(p); flat_barrier((unsigned*)(gp->ws + OFF_BAR));
;     ...
;   run_phase<4>(p); flat_barrier((unsigned*)(gp->ws + OFF_BAR));
;   run_phase<5>(p); flat_barrier((unsigned*)(gp->ws + OFF_BAR));
;   run_phase<6>(p); flat_barrier((unsigned*)(gp->ws + OFF_BAR));
;   run_phase<7>(p); flat_barrier((unsigned*)(gp->ws + OFF_BAR));
;     ...
;   run_phase<8>(p); flat_barrier((unsigned*)(gp->ws + OFF_BAR));
;     ...
;   run_phase<8>(p); flat_barrier((unsigned*)(gp->ws + OFF_BAR));
;   run_phase<9>(p); flat_barrier((unsigned*)(gp->ws + OFF_BAR));
;     ...
;   run_phase<10>(p); flat_barrier((unsigned*)(gp->ws + OFF_BAR));
;     ...
;   run_phase<10>(p); flat_barrier((unsigned*)(gp->ws + OFF_BAR));
;   run_phase<11>(p); flat_barrier((unsigned*)(gp->ws + OFF_BAR));
;   run_phase<12>(p);
; }
amdhsa.kernels:
  - .agpr_count:     0
    .args:
      - .offset:         0
        .size:           168
        .value_kind:     by_value
      - .offset:         168
        .size:           4
        .value_kind:     hidden_block_count_x
      - .offset:         172
        .size:           4
        .value_kind:     hidden_block_count_y
      - .offset:         176
        .size:           4
        .value_kind:     hidden_block_count_z
      - .offset:         180
        .size:           2
        .value_kind:     hidden_group_size_x
      - .offset:         182
        .size:           2
        .value_kind:     hidden_group_size_y
      - .offset:         184
        .size:           2
        .value_kind:     hidden_group_size_z
      - .offset:         186
        .size:           2
        .value_kind:     hidden_remainder_x
      - .offset:         188
        .size:           2
        .value_kind:     hidden_remainder_y
      - .offset:         190
        .size:           2
        .value_kind:     hidden_remainder_z
      - .offset:         208
        .size:           8
        .value_kind:     hidden_global_offset_x
      - .offset:         216
        .size:           8
        .value_kind:     hidden_global_offset_y
      - .offset:         224
        .size:           8
        .value_kind:     hidden_global_offset_z
      - .offset:         232
        .size:           2
        .value_kind:     hidden_grid_dims
      - .offset:         256
        .size:           8
        .value_kind:     hidden_multigrid_sync_arg
    .group_segment_fixed_size: 131072
    .kernarg_segment_align: 8
    .kernarg_segment_size: 424
    .language:       OpenCL C
    .language_version:
      - 2
      - 0
    .max_flat_workgroup_size: 512
    .name:           _Z14fwd_megakernel6Params
    .private_segment_fixed_size: 0
    .sgpr_count:     104
    .sgpr_spill_count: 4
    .symbol:         _Z14fwd_megakernel6Params.kd
    .uniform_work_group_size: 1
    .uses_dynamic_stack: false
    .vgpr_count:     256
    .vgpr_spill_count: 0
    .wavefront_size: 64
